# scanner v2: V/SC LDS reads merged per step pair (ds_read2_b64), first reduction stage via bank-masked DPP adds
# baseline (speedup 1.0000x reference)
.Lscan_entry:
	s_waitcnt vmcnt(0) lgkmcnt(0)
	v_and_b32_e32 v16, 7, v161
	v_lshrrev_b32_e32 v17, 3, v161
	v_lshlrev_b32_e32 v137, 5, v16
	v_lshlrev_b32_e32 v139, 3, v17
	v_lshrrev_b32_e32 v18, 1, v16
	v_and_b32_e32 v19, 1, v16
	v_lshlrev_b32_e32 v18, 8, v18
	v_lshlrev_b32_e32 v19, 2, v19
	v_add3_u32 v84, v139, v18, v19
	v_add_u32_e32 v84, 0x7000, v84
	v_add_u32_e32 v139, 0x5000, v139
	v_mov_b32_e32 v156, 0x8000
	v_cndmask_b32_e64 v128, 0, 1.0, s[42:43]
	v_cndmask_b32_e64 v129, 0, 1.0, s[42:43]
	v_mov_b32_e32 v0, 0
	v_mov_b32_e32 v1, 0
	v_mov_b32_e32 v2, 0
	v_mov_b32_e32 v3, 0
	v_mov_b32_e32 v4, 0
	v_mov_b32_e32 v5, 0
	v_mov_b32_e32 v6, 0
	v_mov_b32_e32 v7, 0
	v_mov_b32_e32 v8, 0
	v_mov_b32_e32 v9, 0
	v_mov_b32_e32 v10, 0
	v_mov_b32_e32 v11, 0
	v_mov_b32_e32 v12, 0
	v_mov_b32_e32 v13, 0
	v_mov_b32_e32 v14, 0
	v_mov_b32_e32 v15, 0
	s_mov_b32 s1, 0
	s_movk_i32 s2, 0x80
	s_barrier
.Lscan_chunk:
	v_add_u32_e32 v130, s1, v137
	v_add_u32_e32 v131, s1, v139
	v_add_u32_e32 v85, s1, v156
	v_add_u32_e32 v86, s1, v84
	s_mov_b32 s0, 4
	ds_read_b128 v[32:35], v130 offset:0
	ds_read_b128 v[36:39], v130 offset:16
	ds_read_b128 v[40:43], v130 offset:4096
	ds_read_b128 v[44:47], v130 offset:4112
	ds_read_b128 v[56:59], v130 offset:12288
	ds_read_b128 v[60:63], v130 offset:12304
	ds_read_b128 v[64:67], v130 offset:16384
	ds_read_b128 v[68:71], v130 offset:16400
	ds_read_b128 v[48:51], v130 offset:8192
	ds_read_b128 v[52:55], v130 offset:8208
	ds_read2_b64 v[72:75], v131 offset0:0 offset1:32
	ds_read2_b64 v[140:143], v85 offset0:0 offset1:2
.Lscan_q4:
	s_waitcnt lgkmcnt(0)
	v_pk_mul_f32 v[16:17], v[2:3], v[34:35]
	v_pk_mul_f32 v[18:19], v[10:11], v[34:35]
	ds_read_b128 v[76:79], v130 offset:256
	v_pk_fma_f32 v[16:17], v[0:1], v[32:33], v[16:17]
	v_pk_fma_f32 v[18:19], v[8:9], v[32:33], v[18:19]
	ds_read_b128 v[80:83], v130 offset:272
	v_pk_fma_f32 v[16:17], v[4:5], v[36:37], v[16:17]
	v_pk_fma_f32 v[18:19], v[12:13], v[36:37], v[18:19]
	ds_read_b128 v[90:93], v130 offset:4352
	v_pk_fma_f32 v[16:17], v[6:7], v[38:39], v[16:17]
	v_pk_fma_f32 v[18:19], v[14:15], v[38:39], v[18:19]
	ds_read_b128 v[94:97], v130 offset:4368
	v_pk_mul_f32 v[20:21], v[2:3], v[42:43]
	v_add_f32_e32 v24, v16, v17
	ds_read_b128 v[112:115], v130 offset:12544
	v_add_f32_e32 v25, v18, v19
	v_pk_mul_f32 v[22:23], v[10:11], v[42:43]
	ds_read_b128 v[116:119], v130 offset:12560
	v_add_f32_dpp v24, v24, v24 quad_perm:[1,0,3,2] row_mask:0xf bank_mask:0xf bound_ctrl:1
	v_add_f32_dpp v25, v25, v25 quad_perm:[1,0,3,2] row_mask:0xf bank_mask:0xf bound_ctrl:1
	ds_read_b128 v[120:123], v130 offset:16640
	v_pk_fma_f32 v[20:21], v[0:1], v[40:41], v[20:21]
	v_add_f32_dpp v24, v24, v24 quad_perm:[2,3,0,1] row_mask:0xf bank_mask:0xf bound_ctrl:1
	ds_read_b128 v[124:127], v130 offset:16656
	v_add_f32_dpp v25, v25, v25 quad_perm:[2,3,0,1] row_mask:0xf bank_mask:0xf bound_ctrl:1
	v_pk_fma_f32 v[22:23], v[8:9], v[40:41], v[22:23]
	ds_read_b128 v[98:101], v130 offset:8448
	v_add_f32_dpp v24, v24, v24 row_half_mirror row_mask:0xf bank_mask:0xf bound_ctrl:1
	v_add_f32_dpp v25, v25, v25 row_half_mirror row_mask:0xf bank_mask:0xf bound_ctrl:1
	ds_read_b128 v[102:105], v130 offset:8464
	v_pk_fma_f32 v[20:21], v[4:5], v[44:45], v[20:21]
	v_pk_fma_f32 v[22:23], v[12:13], v[44:45], v[22:23]
	ds_read2_b64 v[106:109], v131 offset0:64 offset1:96
	v_pk_fma_f32 v[20:21], v[6:7], v[46:47], v[20:21]
	v_pk_fma_f32 v[22:23], v[14:15], v[46:47], v[22:23]
	ds_read2_b64 v[144:147], v85 offset0:4 offset1:6
	v_pk_mul_f32 v[164:165], v[56:57], v[24:25] op_sel_hi:[1,0]
	v_pk_mul_f32 v[166:167], v[56:57], v[24:25] op_sel:[0,1]
	v_pk_mul_f32 v[168:169], v[58:59], v[24:25] op_sel_hi:[1,0]
	v_pk_mul_f32 v[170:171], v[58:59], v[24:25] op_sel:[0,1]
	v_pk_fma_f32 v[164:165], v[64:65], v[72:73], v[164:165] op_sel_hi:[1,0,1]
	v_pk_fma_f32 v[166:167], v[64:65], v[72:73], v[166:167] op_sel:[0,1,0]
	v_pk_fma_f32 v[168:169], v[66:67], v[72:73], v[168:169] op_sel_hi:[1,0,1]
	v_pk_fma_f32 v[170:171], v[66:67], v[72:73], v[170:171] op_sel:[0,1,0]
	v_pk_fma_f32 v[0:1], v[0:1], v[48:49], v[164:165]
	v_pk_fma_f32 v[8:9], v[8:9], v[48:49], v[166:167]
	v_pk_fma_f32 v[2:3], v[2:3], v[50:51], v[168:169]
	v_pk_fma_f32 v[10:11], v[10:11], v[50:51], v[170:171]
	v_pk_mul_f32 v[164:165], v[60:61], v[24:25] op_sel_hi:[1,0]
	v_pk_mul_f32 v[166:167], v[60:61], v[24:25] op_sel:[0,1]
	v_pk_mul_f32 v[168:169], v[62:63], v[24:25] op_sel_hi:[1,0]
	v_pk_mul_f32 v[170:171], v[62:63], v[24:25] op_sel:[0,1]
	v_pk_fma_f32 v[164:165], v[68:69], v[72:73], v[164:165] op_sel_hi:[1,0,1]
	v_pk_fma_f32 v[166:167], v[68:69], v[72:73], v[166:167] op_sel:[0,1,0]
	v_pk_fma_f32 v[168:169], v[70:71], v[72:73], v[168:169] op_sel_hi:[1,0,1]
	v_pk_fma_f32 v[170:171], v[70:71], v[72:73], v[170:171] op_sel:[0,1,0]
	v_pk_fma_f32 v[4:5], v[4:5], v[52:53], v[164:165]
	v_pk_fma_f32 v[12:13], v[12:13], v[52:53], v[166:167]
	v_pk_fma_f32 v[6:7], v[6:7], v[54:55], v[168:169]
	v_pk_fma_f32 v[14:15], v[14:15], v[54:55], v[170:171]
	v_pk_mul_f32 v[164:165], v[24:25], v[140:141] op_sel_hi:[1,0]
	v_pk_mul_f32 v[166:167], v[72:73], v[140:141] op_sel:[0,1]
	v_add_f32_e32 v26, v20, v21
	v_pk_add_f32 v[164:165], v[166:167], v[164:165]
	v_add_f32_e32 v27, v22, v23
	v_pk_fma_f32 v[176:177], v[164:165], v[128:129], v[26:27]
	s_waitcnt lgkmcnt(0)
	v_pk_mul_f32 v[16:17], v[2:3], v[78:79]
	v_pk_mul_f32 v[18:19], v[10:11], v[78:79]
	ds_read_b128 v[32:35], v130 offset:512
	v_pk_fma_f32 v[16:17], v[0:1], v[76:77], v[16:17]
	v_pk_fma_f32 v[18:19], v[8:9], v[76:77], v[18:19]
	ds_read_b128 v[36:39], v130 offset:528
	v_pk_fma_f32 v[16:17], v[4:5], v[80:81], v[16:17]
	v_pk_fma_f32 v[18:19], v[12:13], v[80:81], v[18:19]
	ds_read_b128 v[40:43], v130 offset:4608
	v_pk_fma_f32 v[16:17], v[6:7], v[82:83], v[16:17]
	v_pk_fma_f32 v[18:19], v[14:15], v[82:83], v[18:19]
	ds_read_b128 v[44:47], v130 offset:4624
	v_pk_mul_f32 v[20:21], v[2:3], v[92:93]
	v_add_f32_e32 v24, v16, v17
	ds_read_b128 v[56:59], v130 offset:12800
	v_add_f32_e32 v25, v18, v19
	v_pk_mul_f32 v[22:23], v[10:11], v[92:93]
	ds_read_b128 v[60:63], v130 offset:12816
	v_add_f32_dpp v24, v24, v24 quad_perm:[1,0,3,2] row_mask:0xf bank_mask:0xf bound_ctrl:1
	v_add_f32_dpp v25, v25, v25 quad_perm:[1,0,3,2] row_mask:0xf bank_mask:0xf bound_ctrl:1
	ds_read_b128 v[64:67], v130 offset:16896
	v_pk_fma_f32 v[20:21], v[0:1], v[90:91], v[20:21]
	v_add_f32_dpp v24, v24, v24 quad_perm:[2,3,0,1] row_mask:0xf bank_mask:0xf bound_ctrl:1
	ds_read_b128 v[68:71], v130 offset:16912
	v_add_f32_dpp v25, v25, v25 quad_perm:[2,3,0,1] row_mask:0xf bank_mask:0xf bound_ctrl:1
	v_pk_fma_f32 v[22:23], v[8:9], v[90:91], v[22:23]
	ds_read_b128 v[48:51], v130 offset:8704
	v_add_f32_dpp v24, v24, v24 row_half_mirror row_mask:0xf bank_mask:0xf bound_ctrl:1
	v_add_f32_dpp v25, v25, v25 row_half_mirror row_mask:0xf bank_mask:0xf bound_ctrl:1
	ds_read_b128 v[52:55], v130 offset:8720
	v_pk_fma_f32 v[20:21], v[4:5], v[94:95], v[20:21]
	v_pk_fma_f32 v[22:23], v[12:13], v[94:95], v[22:23]
	v_pk_fma_f32 v[20:21], v[6:7], v[96:97], v[20:21]
	v_pk_fma_f32 v[22:23], v[14:15], v[96:97], v[22:23]
	v_pk_mul_f32 v[164:165], v[112:113], v[24:25] op_sel_hi:[1,0]
	v_pk_mul_f32 v[166:167], v[112:113], v[24:25] op_sel:[0,1]
	v_pk_mul_f32 v[168:169], v[114:115], v[24:25] op_sel_hi:[1,0]
	v_pk_mul_f32 v[170:171], v[114:115], v[24:25] op_sel:[0,1]
	v_pk_fma_f32 v[164:165], v[120:121], v[74:75], v[164:165] op_sel_hi:[1,0,1]
	v_pk_fma_f32 v[166:167], v[120:121], v[74:75], v[166:167] op_sel:[0,1,0]
	v_pk_fma_f32 v[168:169], v[122:123], v[74:75], v[168:169] op_sel_hi:[1,0,1]
	v_pk_fma_f32 v[170:171], v[122:123], v[74:75], v[170:171] op_sel:[0,1,0]
	v_pk_fma_f32 v[0:1], v[0:1], v[98:99], v[164:165]
	v_pk_fma_f32 v[8:9], v[8:9], v[98:99], v[166:167]
	v_pk_fma_f32 v[2:3], v[2:3], v[100:101], v[168:169]
	v_pk_fma_f32 v[10:11], v[10:11], v[100:101], v[170:171]
	v_pk_mul_f32 v[164:165], v[116:117], v[24:25] op_sel_hi:[1,0]
	v_pk_mul_f32 v[166:167], v[116:117], v[24:25] op_sel:[0,1]
	v_pk_mul_f32 v[168:169], v[118:119], v[24:25] op_sel_hi:[1,0]
	v_pk_mul_f32 v[170:171], v[118:119], v[24:25] op_sel:[0,1]
	v_pk_fma_f32 v[164:165], v[124:125], v[74:75], v[164:165] op_sel_hi:[1,0,1]
	v_pk_fma_f32 v[166:167], v[124:125], v[74:75], v[166:167] op_sel:[0,1,0]
	v_pk_fma_f32 v[168:169], v[126:127], v[74:75], v[168:169] op_sel_hi:[1,0,1]
	v_pk_fma_f32 v[170:171], v[126:127], v[74:75], v[170:171] op_sel:[0,1,0]
	v_pk_fma_f32 v[4:5], v[4:5], v[102:103], v[164:165]
	v_pk_fma_f32 v[12:13], v[12:13], v[102:103], v[166:167]
	v_pk_fma_f32 v[6:7], v[6:7], v[104:105], v[168:169]
	v_pk_fma_f32 v[14:15], v[14:15], v[104:105], v[170:171]
	v_pk_mul_f32 v[164:165], v[24:25], v[142:143] op_sel_hi:[1,0]
	v_pk_mul_f32 v[166:167], v[74:75], v[142:143] op_sel:[0,1]
	v_add_f32_e32 v26, v20, v21
	v_pk_add_f32 v[164:165], v[166:167], v[164:165]
	v_add_f32_e32 v27, v22, v23
	v_pk_fma_f32 v[178:179], v[164:165], v[128:129], v[26:27]
	s_waitcnt lgkmcnt(0)
	v_pk_mul_f32 v[16:17], v[2:3], v[34:35]
	v_pk_mul_f32 v[18:19], v[10:11], v[34:35]
	ds_read_b128 v[76:79], v130 offset:768
	v_pk_fma_f32 v[16:17], v[0:1], v[32:33], v[16:17]
	v_pk_fma_f32 v[18:19], v[8:9], v[32:33], v[18:19]
	ds_read_b128 v[80:83], v130 offset:784
	v_pk_fma_f32 v[16:17], v[4:5], v[36:37], v[16:17]
	v_pk_fma_f32 v[18:19], v[12:13], v[36:37], v[18:19]
	ds_read_b128 v[90:93], v130 offset:4864
	v_pk_fma_f32 v[16:17], v[6:7], v[38:39], v[16:17]
	v_pk_fma_f32 v[18:19], v[14:15], v[38:39], v[18:19]
	ds_read_b128 v[94:97], v130 offset:4880
	v_pk_mul_f32 v[20:21], v[2:3], v[42:43]
	v_add_f32_e32 v24, v16, v17
	ds_read_b128 v[112:115], v130 offset:13056
	v_add_f32_e32 v25, v18, v19
	v_pk_mul_f32 v[22:23], v[10:11], v[42:43]
	ds_read_b128 v[116:119], v130 offset:13072
	v_add_f32_dpp v24, v24, v24 quad_perm:[1,0,3,2] row_mask:0xf bank_mask:0xf bound_ctrl:1
	v_add_f32_dpp v25, v25, v25 quad_perm:[1,0,3,2] row_mask:0xf bank_mask:0xf bound_ctrl:1
	ds_read_b128 v[120:123], v130 offset:17152
	v_pk_fma_f32 v[20:21], v[0:1], v[40:41], v[20:21]
	v_add_f32_dpp v24, v24, v24 quad_perm:[2,3,0,1] row_mask:0xf bank_mask:0xf bound_ctrl:1
	ds_read_b128 v[124:127], v130 offset:17168
	v_add_f32_dpp v25, v25, v25 quad_perm:[2,3,0,1] row_mask:0xf bank_mask:0xf bound_ctrl:1
	v_pk_fma_f32 v[22:23], v[8:9], v[40:41], v[22:23]
	ds_read_b128 v[98:101], v130 offset:8960
	v_add_f32_dpp v24, v24, v24 row_half_mirror row_mask:0xf bank_mask:0xf bound_ctrl:1
	v_add_f32_dpp v25, v25, v25 row_half_mirror row_mask:0xf bank_mask:0xf bound_ctrl:1
	ds_read_b128 v[102:105], v130 offset:8976
	v_pk_fma_f32 v[20:21], v[4:5], v[44:45], v[20:21]
	v_pk_fma_f32 v[22:23], v[12:13], v[44:45], v[22:23]
	ds_read2_b64 v[72:75], v131 offset0:128 offset1:160
	v_pk_fma_f32 v[20:21], v[6:7], v[46:47], v[20:21]
	v_pk_fma_f32 v[22:23], v[14:15], v[46:47], v[22:23]
	ds_read2_b64 v[140:143], v85 offset0:8 offset1:10
	v_pk_mul_f32 v[164:165], v[56:57], v[24:25] op_sel_hi:[1,0]
	v_pk_mul_f32 v[166:167], v[56:57], v[24:25] op_sel:[0,1]
	v_pk_mul_f32 v[168:169], v[58:59], v[24:25] op_sel_hi:[1,0]
	v_pk_mul_f32 v[170:171], v[58:59], v[24:25] op_sel:[0,1]
	v_pk_fma_f32 v[164:165], v[64:65], v[106:107], v[164:165] op_sel_hi:[1,0,1]
	v_pk_fma_f32 v[166:167], v[64:65], v[106:107], v[166:167] op_sel:[0,1,0]
	v_pk_fma_f32 v[168:169], v[66:67], v[106:107], v[168:169] op_sel_hi:[1,0,1]
	v_pk_fma_f32 v[170:171], v[66:67], v[106:107], v[170:171] op_sel:[0,1,0]
	v_pk_fma_f32 v[0:1], v[0:1], v[48:49], v[164:165]
	v_pk_fma_f32 v[8:9], v[8:9], v[48:49], v[166:167]
	v_pk_fma_f32 v[2:3], v[2:3], v[50:51], v[168:169]
	v_pk_fma_f32 v[10:11], v[10:11], v[50:51], v[170:171]
	v_pk_mul_f32 v[164:165], v[60:61], v[24:25] op_sel_hi:[1,0]
	v_pk_mul_f32 v[166:167], v[60:61], v[24:25] op_sel:[0,1]
	v_pk_mul_f32 v[168:169], v[62:63], v[24:25] op_sel_hi:[1,0]
	v_pk_mul_f32 v[170:171], v[62:63], v[24:25] op_sel:[0,1]
	v_pk_fma_f32 v[164:165], v[68:69], v[106:107], v[164:165] op_sel_hi:[1,0,1]
	v_pk_fma_f32 v[166:167], v[68:69], v[106:107], v[166:167] op_sel:[0,1,0]
	v_pk_fma_f32 v[168:169], v[70:71], v[106:107], v[168:169] op_sel_hi:[1,0,1]
	v_pk_fma_f32 v[170:171], v[70:71], v[106:107], v[170:171] op_sel:[0,1,0]
	v_pk_fma_f32 v[4:5], v[4:5], v[52:53], v[164:165]
	v_pk_fma_f32 v[12:13], v[12:13], v[52:53], v[166:167]
	v_pk_fma_f32 v[6:7], v[6:7], v[54:55], v[168:169]
	v_pk_fma_f32 v[14:15], v[14:15], v[54:55], v[170:171]
	v_pk_mul_f32 v[164:165], v[24:25], v[144:145] op_sel_hi:[1,0]
	v_pk_mul_f32 v[166:167], v[106:107], v[144:145] op_sel:[0,1]
	v_add_f32_e32 v26, v20, v21
	v_pk_add_f32 v[164:165], v[166:167], v[164:165]
	v_add_f32_e32 v27, v22, v23
	v_pk_fma_f32 v[180:181], v[164:165], v[128:129], v[26:27]
	s_waitcnt lgkmcnt(0)
	v_pk_mul_f32 v[16:17], v[2:3], v[78:79]
	v_pk_mul_f32 v[18:19], v[10:11], v[78:79]
	ds_read_b128 v[32:35], v130 offset:1024
	v_pk_fma_f32 v[16:17], v[0:1], v[76:77], v[16:17]
	v_pk_fma_f32 v[18:19], v[8:9], v[76:77], v[18:19]
	ds_read_b128 v[36:39], v130 offset:1040
	v_pk_fma_f32 v[16:17], v[4:5], v[80:81], v[16:17]
	v_pk_fma_f32 v[18:19], v[12:13], v[80:81], v[18:19]
	ds_read_b128 v[40:43], v130 offset:5120
	v_pk_fma_f32 v[16:17], v[6:7], v[82:83], v[16:17]
	v_pk_fma_f32 v[18:19], v[14:15], v[82:83], v[18:19]
	ds_read_b128 v[44:47], v130 offset:5136
	v_pk_mul_f32 v[20:21], v[2:3], v[92:93]
	v_add_f32_e32 v24, v16, v17
	ds_read_b128 v[56:59], v130 offset:13312
	v_add_f32_e32 v25, v18, v19
	v_pk_mul_f32 v[22:23], v[10:11], v[92:93]
	ds_read_b128 v[60:63], v130 offset:13328
	v_add_f32_dpp v24, v24, v24 quad_perm:[1,0,3,2] row_mask:0xf bank_mask:0xf bound_ctrl:1
	v_add_f32_dpp v25, v25, v25 quad_perm:[1,0,3,2] row_mask:0xf bank_mask:0xf bound_ctrl:1
	ds_read_b128 v[64:67], v130 offset:17408
	v_pk_fma_f32 v[20:21], v[0:1], v[90:91], v[20:21]
	v_add_f32_dpp v24, v24, v24 quad_perm:[2,3,0,1] row_mask:0xf bank_mask:0xf bound_ctrl:1
	ds_read_b128 v[68:71], v130 offset:17424
	v_add_f32_dpp v25, v25, v25 quad_perm:[2,3,0,1] row_mask:0xf bank_mask:0xf bound_ctrl:1
	v_pk_fma_f32 v[22:23], v[8:9], v[90:91], v[22:23]
	ds_read_b128 v[48:51], v130 offset:9216
	v_add_f32_dpp v24, v24, v24 row_half_mirror row_mask:0xf bank_mask:0xf bound_ctrl:1
	v_add_f32_dpp v25, v25, v25 row_half_mirror row_mask:0xf bank_mask:0xf bound_ctrl:1
	ds_read_b128 v[52:55], v130 offset:9232
	v_pk_fma_f32 v[20:21], v[4:5], v[94:95], v[20:21]
	v_pk_fma_f32 v[22:23], v[12:13], v[94:95], v[22:23]
	v_pk_fma_f32 v[20:21], v[6:7], v[96:97], v[20:21]
	v_pk_fma_f32 v[22:23], v[14:15], v[96:97], v[22:23]
	v_pk_mul_f32 v[164:165], v[112:113], v[24:25] op_sel_hi:[1,0]
	v_pk_mul_f32 v[166:167], v[112:113], v[24:25] op_sel:[0,1]
	v_pk_mul_f32 v[168:169], v[114:115], v[24:25] op_sel_hi:[1,0]
	v_pk_mul_f32 v[170:171], v[114:115], v[24:25] op_sel:[0,1]
	v_pk_fma_f32 v[164:165], v[120:121], v[108:109], v[164:165] op_sel_hi:[1,0,1]
	v_pk_fma_f32 v[166:167], v[120:121], v[108:109], v[166:167] op_sel:[0,1,0]
	v_pk_fma_f32 v[168:169], v[122:123], v[108:109], v[168:169] op_sel_hi:[1,0,1]
	v_pk_fma_f32 v[170:171], v[122:123], v[108:109], v[170:171] op_sel:[0,1,0]
	v_pk_fma_f32 v[0:1], v[0:1], v[98:99], v[164:165]
	v_pk_fma_f32 v[8:9], v[8:9], v[98:99], v[166:167]
	v_pk_fma_f32 v[2:3], v[2:3], v[100:101], v[168:169]
	v_pk_fma_f32 v[10:11], v[10:11], v[100:101], v[170:171]
	v_pk_mul_f32 v[164:165], v[116:117], v[24:25] op_sel_hi:[1,0]
	v_pk_mul_f32 v[166:167], v[116:117], v[24:25] op_sel:[0,1]
	v_pk_mul_f32 v[168:169], v[118:119], v[24:25] op_sel_hi:[1,0]
	v_pk_mul_f32 v[170:171], v[118:119], v[24:25] op_sel:[0,1]
	v_pk_fma_f32 v[164:165], v[124:125], v[108:109], v[164:165] op_sel_hi:[1,0,1]
	v_pk_fma_f32 v[166:167], v[124:125], v[108:109], v[166:167] op_sel:[0,1,0]
	v_pk_fma_f32 v[168:169], v[126:127], v[108:109], v[168:169] op_sel_hi:[1,0,1]
	v_pk_fma_f32 v[170:171], v[126:127], v[108:109], v[170:171] op_sel:[0,1,0]
	v_pk_fma_f32 v[4:5], v[4:5], v[102:103], v[164:165]
	v_pk_fma_f32 v[12:13], v[12:13], v[102:103], v[166:167]
	v_pk_fma_f32 v[6:7], v[6:7], v[104:105], v[168:169]
	v_pk_fma_f32 v[14:15], v[14:15], v[104:105], v[170:171]
	v_pk_mul_f32 v[164:165], v[24:25], v[146:147] op_sel_hi:[1,0]
	v_pk_mul_f32 v[166:167], v[108:109], v[146:147] op_sel:[0,1]
	v_add_f32_e32 v26, v20, v21
	v_pk_add_f32 v[164:165], v[166:167], v[164:165]
	v_add_f32_e32 v27, v22, v23
	v_pk_fma_f32 v[182:183], v[164:165], v[128:129], v[26:27]
	v_add_f32_dpp v176, v176, v176 row_half_mirror row_mask:0xf bank_mask:0x5
	v_add_f32_dpp v176, v180, v180 row_half_mirror row_mask:0xf bank_mask:0xa
	v_add_f32_dpp v177, v177, v177 row_half_mirror row_mask:0xf bank_mask:0x5
	v_add_f32_dpp v177, v181, v181 row_half_mirror row_mask:0xf bank_mask:0xa
	v_add_f32_dpp v178, v178, v178 row_half_mirror row_mask:0xf bank_mask:0x5
	v_add_f32_dpp v178, v182, v182 row_half_mirror row_mask:0xf bank_mask:0xa
	v_add_f32_dpp v179, v179, v179 row_half_mirror row_mask:0xf bank_mask:0x5
	v_add_f32_dpp v179, v183, v183 row_half_mirror row_mask:0xf bank_mask:0xa
	v_cndmask_b32_e64 v16, v178, v176, s[46:47]
	v_cndmask_b32_e64 v17, v176, v178, s[46:47]
	v_cndmask_b32_e64 v18, v179, v177, s[46:47]
	v_cndmask_b32_e64 v19, v177, v179, s[46:47]
	v_add_u32_e32 v130, 0x400, v130
	v_add_f32_dpp v176, v17, v16 quad_perm:[2,3,0,1] row_mask:0xf bank_mask:0xf bound_ctrl:1
	v_add_u32_e32 v131, 0x400, v131
	v_add_f32_dpp v177, v19, v18 quad_perm:[2,3,0,1] row_mask:0xf bank_mask:0xf bound_ctrl:1
	v_add_u32_e32 v85, 64, v85
	v_cndmask_b32_e64 v16, v177, v176, s[48:49]
	v_cndmask_b32_e64 v17, v176, v177, s[48:49]
	s_add_i32 s0, s0, -1
	s_cmp_lg_u32 s0, 0
	v_add_f32_dpp v18, v17, v16 quad_perm:[1,0,3,2] row_mask:0xf bank_mask:0xf bound_ctrl:1
	s_nop 0
	ds_write_b32 v86, v18
	v_add_u32_e32 v86, 0x400, v86
	s_cbranch_scc1 .Lscan_q4
	s_xor_b32 s1, s1, 0x8200
	s_add_i32 s2, s2, -1
	s_waitcnt lgkmcnt(0)
	s_barrier
	s_cmp_lg_u32 s2, 0
	s_cbranch_scc1 .Lscan_chunk
	s_branch .LBB0_627
